# post pass as a rolling two-slot pipeline: the next row of a slot is loaded right after its stores, while the other slot computes
# speedup vs baseline: 1.0058x; 1.0058x over previous
.Lpost_setupdone:
	v_readfirstlane_b32 s0, v214
	s_nop 0
	s_lshl_b32 s0, s0, 1
	s_add_u32 s1, s0, 1
	s_mov_b32 s83, 0
	s_mov_b32 s72, 0
	s_cmp_ge_u32 s0, 33280
	s_cbranch_scc1 .Lp3_prepA0_done
	s_mov_b32 s83, 1
	s_mov_b32 s2, 0
	s_cmp_ge_u32 s0, 8320
	s_addc_u32 s2, s2, 0
	s_cmp_ge_u32 s0, 16640
	s_addc_u32 s2, s2, 0
	s_cmp_ge_u32 s0, 24960
	s_addc_u32 s2, s2, 0
	s_mulk_i32 s2, 0x2080
	s_sub_u32 s18, s0, s2
	s_lshr_b32 s2, s2, 6
	s_mov_b32 s10, 0
	s_cmp_ge_u32 s0, 8320
	s_addc_u32 s10, s10, 0
	s_cmp_ge_u32 s0, 16640
	s_addc_u32 s10, s10, 0
	s_cmp_ge_u32 s0, 24960
	s_addc_u32 s10, s10, 0
	s_lshl_b32 s6, s0, 6
	s_lshl_b32 s2, s10, 13
	s_add_u32 s2, s2, s18
	s_sub_u32 s2, s2, 0x80
	s_mul_i32 s3, s10, s15
	s_add_u32 s3, s3, s18
	s_sub_u32 s3, s3, 0x70
	s_lshl_b32 s10, s10, 4
	s_add_u32 s10, s10, s18
	s_sub_u32 s10, s10, 0x70
	s_cmp_lt_u32 s18, 0x80
	s_cselect_b32 s74, s70, s68
	s_cselect_b32 s75, s71, s69
	s_cselect_b32 s3, s3, s2
	s_cselect_b32 s76, s62, s54
	s_cselect_b32 s77, s63, s55
	s_cselect_b32 s2, s10, s2
	s_lshl_b32 s3, s3, 12
	s_lshl_b32 s2, s2, 12
	s_add_u32 s74, s74, s3
	s_addc_u32 s75, s75, 0
	s_add_u32 s76, s76, s2
	s_addc_u32 s77, s77, 0
	v_add_u32_e32 v44, s6, v41
	v_add_u32_e32 v45, 0x1040000, v44
	v_add_u32_e32 v46, 0x2080000, v44
	v_add_u32_e32 v47, 0x30c0000, v44
	s_cmp_ge_u32 s18, s11
	s_cselect_b32 s72, 1, 0
	s_cbranch_scc0 .Lp3_prepA0_done
	global_load_dwordx2 v[0:1], v44, s[58:59]
	global_load_dwordx2 v[2:3], v45, s[58:59]
	global_load_dwordx2 v[4:5], v46, s[58:59]
	global_load_dwordx2 v[6:7], v47, s[58:59]
	global_load_dwordx4 v[8:11], v40, s[74:75] offset:0
	global_load_dwordx4 v[12:15], v40, s[74:75] offset:1024
	global_load_dwordx4 v[16:19], v40, s[74:75] offset:2048
	global_load_dwordx4 v[20:23], v40, s[74:75] offset:3072
.Lp3_prepA0_done:
	s_mov_b32 s82, 0
	s_mov_b32 s73, 0
	s_cmp_ge_u32 s1, 33280
	s_cbranch_scc1 .Lp3_prepB0_done
	s_mov_b32 s82, 1
	s_mov_b32 s2, 0
	s_cmp_ge_u32 s1, 8320
	s_addc_u32 s2, s2, 0
	s_cmp_ge_u32 s1, 16640
	s_addc_u32 s2, s2, 0
	s_cmp_ge_u32 s1, 24960
	s_addc_u32 s2, s2, 0
	s_mulk_i32 s2, 0x2080
	s_sub_u32 s19, s1, s2
	s_lshr_b32 s2, s2, 6
	s_mov_b32 s10, 0
	s_cmp_ge_u32 s1, 8320
	s_addc_u32 s10, s10, 0
	s_cmp_ge_u32 s1, 16640
	s_addc_u32 s10, s10, 0
	s_cmp_ge_u32 s1, 24960
	s_addc_u32 s10, s10, 0
	s_lshl_b32 s7, s1, 6
	s_lshl_b32 s2, s10, 13
	s_add_u32 s2, s2, s19
	s_sub_u32 s2, s2, 0x80
	s_mul_i32 s3, s10, s15
	s_add_u32 s3, s3, s19
	s_sub_u32 s3, s3, 0x70
	s_lshl_b32 s10, s10, 4
	s_add_u32 s10, s10, s19
	s_sub_u32 s10, s10, 0x70
	s_cmp_lt_u32 s19, 0x80
	s_cselect_b32 s78, s70, s68
	s_cselect_b32 s79, s71, s69
	s_cselect_b32 s3, s3, s2
	s_cselect_b32 s80, s62, s54
	s_cselect_b32 s81, s63, s55
	s_cselect_b32 s2, s10, s2
	s_lshl_b32 s3, s3, 12
	s_lshl_b32 s2, s2, 12
	s_add_u32 s78, s78, s3
	s_addc_u32 s79, s79, 0
	s_add_u32 s80, s80, s2
	s_addc_u32 s81, s81, 0
	v_add_u32_e32 v48, s7, v41
	v_add_u32_e32 v49, 0x1040000, v48
	v_add_u32_e32 v50, 0x2080000, v48
	v_add_u32_e32 v51, 0x30c0000, v48
	s_cmp_ge_u32 s19, s11
	s_cselect_b32 s73, 1, 0
	s_cbranch_scc0 .Lp3_prepB0_done
	global_load_dwordx2 v[24:25], v48, s[58:59]
	global_load_dwordx2 v[26:27], v49, s[58:59]
	global_load_dwordx2 v[28:29], v50, s[58:59]
	global_load_dwordx2 v[30:31], v51, s[58:59]
	global_load_dwordx4 v[92:95], v40, s[78:79] offset:0
	global_load_dwordx4 v[96:99], v40, s[78:79] offset:1024
	global_load_dwordx4 v[100:103], v40, s[78:79] offset:2048
	global_load_dwordx4 v[104:107], v40, s[78:79] offset:3072
.Lp3_prepB0_done:
.Lpost_loop:
	s_cmp_eq_u32 s83, 0
	s_cbranch_scc1 .Lp3_slotA_done
	s_cmp_eq_u32 s72, 0
	s_cbranch_scc1 .Lp3_zA
	s_cmp_eq_u32 s73, 0
	s_cbranch_scc1 .Lp3_w0A
	s_waitcnt vmcnt(8)
	s_branch .Lp3_cA

.Lpost_cA_done:
	global_store_dwordx4 v40, v[8:11], s[76:77] offset:0
	global_store_dwordx4 v40, v[12:15], s[76:77] offset:1024
	global_store_dwordx4 v40, v[16:19], s[76:77] offset:2048
	global_store_dwordx4 v40, v[20:23], s[76:77] offset:3072
	s_cmp_lg_u32 s14, 0
	s_cbranch_scc1 .Lpost_sA_done
	global_store_dwordx2 v44, v[0:1], s[58:59]
	global_store_dwordx2 v45, v[2:3], s[58:59]
	global_store_dwordx2 v46, v[4:5], s[58:59]
	global_store_dwordx2 v47, v[6:7], s[58:59]

.Lp3_advA:
	s_add_u32 s0, s0, 0x1000
	s_mov_b32 s83, 0
	s_mov_b32 s72, 0
	s_cmp_ge_u32 s0, 33280
	s_cbranch_scc1 .Lp3_prepAn_done
	s_mov_b32 s83, 1
	s_mov_b32 s2, 0
	s_cmp_ge_u32 s0, 8320
	s_addc_u32 s2, s2, 0
	s_cmp_ge_u32 s0, 16640
	s_addc_u32 s2, s2, 0
	s_cmp_ge_u32 s0, 24960
	s_addc_u32 s2, s2, 0
	s_mulk_i32 s2, 0x2080
	s_sub_u32 s18, s0, s2
	s_lshr_b32 s2, s2, 6
	s_mov_b32 s10, 0
	s_cmp_ge_u32 s0, 8320
	s_addc_u32 s10, s10, 0
	s_cmp_ge_u32 s0, 16640
	s_addc_u32 s10, s10, 0
	s_cmp_ge_u32 s0, 24960
	s_addc_u32 s10, s10, 0
	s_lshl_b32 s6, s0, 6
	s_lshl_b32 s2, s10, 13
	s_add_u32 s2, s2, s18
	s_sub_u32 s2, s2, 0x80
	s_mul_i32 s3, s10, s15
	s_add_u32 s3, s3, s18
	s_sub_u32 s3, s3, 0x70
	s_lshl_b32 s10, s10, 4
	s_add_u32 s10, s10, s18
	s_sub_u32 s10, s10, 0x70
	s_cmp_lt_u32 s18, 0x80
	s_cselect_b32 s74, s70, s68
	s_cselect_b32 s75, s71, s69
	s_cselect_b32 s3, s3, s2
	s_cselect_b32 s76, s62, s54
	s_cselect_b32 s77, s63, s55
	s_cselect_b32 s2, s10, s2
	s_lshl_b32 s3, s3, 12
	s_lshl_b32 s2, s2, 12
	s_add_u32 s74, s74, s3
	s_addc_u32 s75, s75, 0
	s_add_u32 s76, s76, s2
	s_addc_u32 s77, s77, 0
	v_add_u32_e32 v44, s6, v41
	v_add_u32_e32 v45, 0x1040000, v44
	v_add_u32_e32 v46, 0x2080000, v44
	v_add_u32_e32 v47, 0x30c0000, v44
	s_cmp_ge_u32 s18, s11
	s_cselect_b32 s72, 1, 0
	s_cbranch_scc0 .Lp3_prepAn_done
	global_load_dwordx2 v[0:1], v44, s[58:59]
	global_load_dwordx2 v[2:3], v45, s[58:59]
	global_load_dwordx2 v[4:5], v46, s[58:59]
	global_load_dwordx2 v[6:7], v47, s[58:59]
	global_load_dwordx4 v[8:11], v40, s[74:75] offset:0
	global_load_dwordx4 v[12:15], v40, s[74:75] offset:1024
	global_load_dwordx4 v[16:19], v40, s[74:75] offset:2048
	global_load_dwordx4 v[20:23], v40, s[74:75] offset:3072
.Lp3_prepAn_done:
.Lp3_slotA_done:
	s_cmp_eq_u32 s82, 0
	s_cbranch_scc1 .Lp3_slotB_done
	s_cmp_eq_u32 s73, 0
	s_cbranch_scc1 .Lp3_zB
	s_cmp_eq_u32 s72, 0
	s_cbranch_scc1 .Lp3_w0B
	s_waitcnt vmcnt(8)
	s_branch .Lp3_cB

.Lp3_cB:
	v_lshlrev_b32_e32 v124, 16, v24
	v_and_b32_e32 v125, 0xffff0000, v24
	v_lshlrev_b32_e32 v126, 16, v25
	v_and_b32_e32 v127, 0xffff0000, v25
	v_lshlrev_b32_e32 v128, 16, v26
	v_and_b32_e32 v129, 0xffff0000, v26
	v_lshlrev_b32_e32 v130, 16, v27
	v_and_b32_e32 v131, 0xffff0000, v27
	v_lshlrev_b32_e32 v132, 16, v28
	v_and_b32_e32 v133, 0xffff0000, v28
	v_lshlrev_b32_e32 v134, 16, v29
	v_and_b32_e32 v135, 0xffff0000, v29
	v_lshlrev_b32_e32 v136, 16, v30
	v_and_b32_e32 v137, 0xffff0000, v30
	v_lshlrev_b32_e32 v138, 16, v31
	v_and_b32_e32 v139, 0xffff0000, v31
	v_mul_f32_e32 v59, v124, v124
	v_mul_f32_e32 v58, v125, v125
	v_fmac_f32_e32 v59, v126, v126
	v_fmac_f32_e32 v58, v127, v127
	v_fmac_f32_e32 v59, v128, v128
	v_fmac_f32_e32 v58, v129, v129
	v_fmac_f32_e32 v59, v130, v130
	v_fmac_f32_e32 v58, v131, v131
	v_fmac_f32_e32 v59, v132, v132
	v_fmac_f32_e32 v58, v133, v133
	v_fmac_f32_e32 v59, v134, v134
	v_fmac_f32_e32 v58, v135, v135
	v_fmac_f32_e32 v59, v136, v136
	v_fmac_f32_e32 v58, v137, v137
	v_fmac_f32_e32 v59, v138, v138
	v_fmac_f32_e32 v58, v139, v139
	v_add_f32_e32 v59, v59, v58
	s_nop 1
	v_add_f32_dpp v59, v59, v59 quad_perm:[1,0,3,2] row_mask:0xf bank_mask:0xf
	s_nop 1
	v_add_f32_dpp v59, v59, v59 quad_perm:[2,3,0,1] row_mask:0xf bank_mask:0xf
	s_nop 1
	v_add_f32_dpp v59, v59, v59 row_half_mirror row_mask:0xf bank_mask:0xf
	s_nop 1
	v_add_f32_dpp v59, v59, v59 row_ror:8 row_mask:0xf bank_mask:0xf
	ds_bpermute_b32 v58, v42, v59
	s_waitcnt lgkmcnt(0)
	v_add_f32_e32 v59, v59, v58
	ds_bpermute_b32 v58, v43, v59
	s_waitcnt lgkmcnt(0)
	v_add_f32_e32 v59, v59, v58
	v_fmamk_f32 v59, v59, 0x3a800000, v221
	v_rsq_f32_e32 v59, v59
	s_nop 0
	v_mul_f32_e32 v124, v59, v124
	v_fma_f32 v92, v124, v60, v92
	v_mul_f32_e32 v125, v59, v125
	v_fma_f32 v93, v125, v61, v93
	v_mul_f32_e32 v126, v59, v126
	v_fma_f32 v94, v126, v62, v94
	v_mul_f32_e32 v127, v59, v127
	v_fma_f32 v95, v127, v63, v95
	v_mul_f32_e32 v128, v59, v128
	v_fma_f32 v96, v128, v64, v96
	v_mul_f32_e32 v129, v59, v129
	v_fma_f32 v97, v129, v65, v97
	v_mul_f32_e32 v130, v59, v130
	v_fma_f32 v98, v130, v66, v98
	v_mul_f32_e32 v131, v59, v131
	v_fma_f32 v99, v131, v67, v99
	v_mul_f32_e32 v132, v59, v132
	v_fma_f32 v100, v132, v68, v100
	v_mul_f32_e32 v133, v59, v133
	v_fma_f32 v101, v133, v69, v101
	v_mul_f32_e32 v134, v59, v134
	v_fma_f32 v102, v134, v70, v102
	v_mul_f32_e32 v135, v59, v135
	v_fma_f32 v103, v135, v71, v103
	v_mul_f32_e32 v136, v59, v136
	v_fma_f32 v104, v136, v72, v104
	v_mul_f32_e32 v137, v59, v137
	v_fma_f32 v105, v137, v73, v105
	v_mul_f32_e32 v138, v59, v138
	v_fma_f32 v106, v138, v74, v106
	v_mul_f32_e32 v139, v59, v139
	v_fma_f32 v107, v139, v75, v107
	s_cmp_lg_u32 s14, 0
	s_cbranch_scc1 .Lpost_cB_done
	v_mul_f32_e32 v59, v92, v92
	v_mul_f32_e32 v58, v93, v93
	v_fmac_f32_e32 v59, v94, v94
	v_fmac_f32_e32 v58, v95, v95
	v_fmac_f32_e32 v59, v96, v96
	v_fmac_f32_e32 v58, v97, v97
	v_fmac_f32_e32 v59, v98, v98
	v_fmac_f32_e32 v58, v99, v99
	v_fmac_f32_e32 v59, v100, v100
	v_fmac_f32_e32 v58, v101, v101
	v_fmac_f32_e32 v59, v102, v102
	v_fmac_f32_e32 v58, v103, v103
	v_fmac_f32_e32 v59, v104, v104
	v_fmac_f32_e32 v58, v105, v105
	v_fmac_f32_e32 v59, v106, v106
	v_fmac_f32_e32 v58, v107, v107
	v_add_f32_e32 v59, v59, v58
	s_nop 1
	v_add_f32_dpp v59, v59, v59 quad_perm:[1,0,3,2] row_mask:0xf bank_mask:0xf
	s_nop 1
	v_add_f32_dpp v59, v59, v59 quad_perm:[2,3,0,1] row_mask:0xf bank_mask:0xf
	s_nop 1
	v_add_f32_dpp v59, v59, v59 row_half_mirror row_mask:0xf bank_mask:0xf
	s_nop 1
	v_add_f32_dpp v59, v59, v59 row_ror:8 row_mask:0xf bank_mask:0xf
	ds_bpermute_b32 v58, v42, v59
	s_waitcnt lgkmcnt(0)
	v_add_f32_e32 v59, v59, v58
	ds_bpermute_b32 v58, v43, v59
	s_waitcnt lgkmcnt(0)
	v_add_f32_e32 v59, v59, v58
	v_fmamk_f32 v59, v59, 0x3a800000, v221
	v_rsq_f32_e32 v59, v59
	s_nop 0
	v_mul_f32_e32 v124, v92, v59
	v_mul_f32_e32 v124, v76, v124
	v_mul_f32_e32 v125, v93, v59
	v_mul_f32_e32 v125, v77, v125
	v_mul_f32_e32 v126, v94, v59
	v_mul_f32_e32 v126, v78, v126
	v_mul_f32_e32 v127, v95, v59
	v_mul_f32_e32 v127, v79, v127
	v_mul_f32_e32 v128, v96, v59
	v_mul_f32_e32 v128, v80, v128
	v_mul_f32_e32 v129, v97, v59
	v_mul_f32_e32 v129, v81, v129
	v_mul_f32_e32 v130, v98, v59
	v_mul_f32_e32 v130, v82, v130
	v_mul_f32_e32 v131, v99, v59
	v_mul_f32_e32 v131, v83, v131
	v_mul_f32_e32 v132, v100, v59
	v_mul_f32_e32 v132, v84, v132
	v_mul_f32_e32 v133, v101, v59
	v_mul_f32_e32 v133, v85, v133
	v_mul_f32_e32 v134, v102, v59
	v_mul_f32_e32 v134, v86, v134
	v_mul_f32_e32 v135, v103, v59
	v_mul_f32_e32 v135, v87, v135
	v_mul_f32_e32 v136, v104, v59
	v_mul_f32_e32 v136, v88, v136
	v_mul_f32_e32 v137, v105, v59
	v_mul_f32_e32 v137, v89, v137
	v_mul_f32_e32 v138, v106, v59
	v_mul_f32_e32 v138, v90, v138
	v_mul_f32_e32 v139, v107, v59
	v_mul_f32_e32 v139, v91, v139
	v_cvt_pk_bf16_f32 v24, v124, v125
	v_cvt_pk_bf16_f32 v25, v126, v127
	v_cvt_pk_bf16_f32 v26, v128, v129
	v_cvt_pk_bf16_f32 v27, v130, v131
	v_cvt_pk_bf16_f32 v28, v132, v133
	v_cvt_pk_bf16_f32 v29, v134, v135
	v_cvt_pk_bf16_f32 v30, v136, v137
	v_cvt_pk_bf16_f32 v31, v138, v139
.Lpost_cB_done:
	global_store_dwordx4 v40, v[92:95], s[80:81] offset:0
	global_store_dwordx4 v40, v[96:99], s[80:81] offset:1024
	global_store_dwordx4 v40, v[100:103], s[80:81] offset:2048
	global_store_dwordx4 v40, v[104:107], s[80:81] offset:3072
	s_cmp_lg_u32 s14, 0
	s_cbranch_scc1 .Lpost_sB_done
	global_store_dwordx2 v48, v[24:25], s[58:59]
	global_store_dwordx2 v49, v[26:27], s[58:59]
	global_store_dwordx2 v50, v[28:29], s[58:59]
	global_store_dwordx2 v51, v[30:31], s[58:59]

.Lp3_zB:
	s_cmp_lg_u32 s14, 0
	s_cbranch_scc1 .Lp3_advB
	global_store_dwordx2 v48, v[52:53], s[58:59]
	global_store_dwordx2 v49, v[52:53], s[58:59]
	global_store_dwordx2 v50, v[52:53], s[58:59]
	global_store_dwordx2 v51, v[52:53], s[58:59]
.Lp3_advB:
	s_add_u32 s1, s1, 0x1000
	s_mov_b32 s82, 0
	s_mov_b32 s73, 0
	s_cmp_ge_u32 s1, 33280
	s_cbranch_scc1 .Lp3_prepBn_done
	s_mov_b32 s82, 1
	s_mov_b32 s2, 0
	s_cmp_ge_u32 s1, 8320
	s_addc_u32 s2, s2, 0
	s_cmp_ge_u32 s1, 16640
	s_addc_u32 s2, s2, 0
	s_cmp_ge_u32 s1, 24960
	s_addc_u32 s2, s2, 0
	s_mulk_i32 s2, 0x2080
	s_sub_u32 s19, s1, s2
	s_lshr_b32 s2, s2, 6
	s_mov_b32 s10, 0
	s_cmp_ge_u32 s1, 8320
	s_addc_u32 s10, s10, 0
	s_cmp_ge_u32 s1, 16640
	s_addc_u32 s10, s10, 0
	s_cmp_ge_u32 s1, 24960
	s_addc_u32 s10, s10, 0
	s_lshl_b32 s7, s1, 6
	s_lshl_b32 s2, s10, 13
	s_add_u32 s2, s2, s19
	s_sub_u32 s2, s2, 0x80
	s_mul_i32 s3, s10, s15
	s_add_u32 s3, s3, s19
	s_sub_u32 s3, s3, 0x70
	s_lshl_b32 s10, s10, 4
	s_add_u32 s10, s10, s19
	s_sub_u32 s10, s10, 0x70
	s_cmp_lt_u32 s19, 0x80
	s_cselect_b32 s78, s70, s68
	s_cselect_b32 s79, s71, s69
	s_cselect_b32 s3, s3, s2
	s_cselect_b32 s80, s62, s54
	s_cselect_b32 s81, s63, s55
	s_cselect_b32 s2, s10, s2
	s_lshl_b32 s3, s3, 12
	s_lshl_b32 s2, s2, 12
	s_add_u32 s78, s78, s3
	s_addc_u32 s79, s79, 0
	s_add_u32 s80, s80, s2
	s_addc_u32 s81, s81, 0
	v_add_u32_e32 v48, s7, v41
	v_add_u32_e32 v49, 0x1040000, v48
	v_add_u32_e32 v50, 0x2080000, v48
	v_add_u32_e32 v51, 0x30c0000, v48
	s_cmp_ge_u32 s19, s11
	s_cselect_b32 s73, 1, 0
	s_cbranch_scc0 .Lp3_prepBn_done
	global_load_dwordx2 v[24:25], v48, s[58:59]
	global_load_dwordx2 v[26:27], v49, s[58:59]
	global_load_dwordx2 v[28:29], v50, s[58:59]
	global_load_dwordx2 v[30:31], v51, s[58:59]
	global_load_dwordx4 v[92:95], v40, s[78:79] offset:0
	global_load_dwordx4 v[96:99], v40, s[78:79] offset:1024
	global_load_dwordx4 v[100:103], v40, s[78:79] offset:2048
	global_load_dwordx4 v[104:107], v40, s[78:79] offset:3072
.Lp3_prepBn_done:
.Lp3_slotB_done:
	s_or_b32 s2, s83, s82
	s_cmp_lg_u32 s2, 0
	s_cbranch_scc1 .Lpost_loop
	s_waitcnt vmcnt(0)
